# cache policy: nt (streaming) hint on the read-once residual-row loads of phase_norm / phase_final and on the final output stores, on top of v24
# speedup vs baseline: 1.0112x; 1.0112x over previous
; __device__ __forceinline__ void phase_norm(PP p, int l, const float* mod, int lane, int wave) {
;     ...
;     for (int row = gw; row < MTOK; row += NGW) {
;         const int b = row >> 12;
;         const f32x4* xr = (const f32x4*)(xin + (size_t)row * DM) + lane;
;         f32x4 v[8]; float s = 0.f;
; #pragma unroll
;         for (int j = 0; j < 8; ++j) { v[j] = xr[64 * j]; s += (v[j].x * v[j].x + v[j].y * v[j].y) + (v[j].z * v[j].z + v[j].w * v[j].w); }
;         s = wave_sum(s);
;         const float rstd = 1.f / sqrtf(s * (1.f / DM) + RMS_EPS);
.LBB0_135:
	s_mov_b64 s[2:3], s[68:69]
	s_mov_b32 s4, s80
	s_add_i32 s4, s4, s81
	s_mov_b32 s5, s77
	s_cmpk_gt_i32 s4, 0x3fff
	s_mul_i32 s16, s60, 0x18000
	s_cbranch_scc1 .LBB0_138
	s_load_dwordx2 s[10:11], s[68:69], 0x88
	s_load_dwordx2 s[12:13], s[68:69], 0x10
	s_cmp_eq_u32 s60, 0
	s_cselect_b32 s5, 0, 0x80
	s_add_u32 s2, s68, s5
	s_addc_u32 s3, s69, 0
	v_lshlrev_b32_e32 v160, 4, v239
	v_lshlrev_b32_e32 v161, 3, v239
	v_xor_b32_e32 v162, 1, v239
	v_xor_b32_e32 v163, 2, v239
	v_xor_b32_e32 v164, 4, v239
	v_xor_b32_e32 v165, 8, v239
	v_xor_b32_e32 v166, 16, v239
	v_xor_b32_e32 v167, 32, v239
	v_lshlrev_b32_e32 v162, 2, v162
	v_lshlrev_b32_e32 v163, 2, v163
	v_lshlrev_b32_e32 v164, 2, v164
	v_lshlrev_b32_e32 v165, 2, v165
	v_lshlrev_b32_e32 v166, 2, v166
	v_lshlrev_b32_e32 v167, 2, v167
	s_load_dwordx2 s[2:3], s[2:3], 0x0
	s_waitcnt lgkmcnt(0)
	s_add_u32 s6, s10, s16
	s_addc_u32 s7, s11, 0
	s_add_u32 s6, s6, 0x2000
	s_addc_u32 s7, s7, 0
	s_add_u32 s8, s10, 0x7100000
	s_addc_u32 s9, s11, 0
	s_lshl_b32 s5, s60, 13
	s_add_u32 s12, s12, s5
	s_addc_u32 s13, s13, 0
	s_add_u32 s12, s12, 0x1000
	s_addc_u32 s13, s13, 0
	s_add_u32 s2, s2, 0x1000
	s_addc_u32 s3, s3, 0
	s_lshl_b32 s5, s4, 13
	s_add_u32 s14, s2, s5
	s_addc_u32 s15, s3, 0
	global_load_dwordx4 v[0:3], v160, s[14:15] offset:-4096 nt
	global_load_dwordx4 v[4:7], v160, s[14:15] offset:-3072 nt
	global_load_dwordx4 v[8:11], v160, s[14:15] offset:-2048 nt
	global_load_dwordx4 v[12:15], v160, s[14:15] offset:-1024 nt
	global_load_dwordx4 v[16:19], v160, s[14:15] offset:0 nt
	global_load_dwordx4 v[20:23], v160, s[14:15] offset:1024 nt
	global_load_dwordx4 v[24:27], v160, s[14:15] offset:2048 nt
	global_load_dwordx4 v[28:31], v160, s[14:15] offset:3072 nt
	global_load_dwordx4 v[64:67], v160, s[12:13] offset:-4096
	global_load_dwordx4 v[68:71], v160, s[12:13] offset:-3072
	global_load_dwordx4 v[72:75], v160, s[12:13] offset:-2048
	global_load_dwordx4 v[76:79], v160, s[12:13] offset:-1024
	global_load_dwordx4 v[80:83], v160, s[12:13] offset:0
	global_load_dwordx4 v[84:87], v160, s[12:13] offset:1024
	global_load_dwordx4 v[88:91], v160, s[12:13] offset:2048
	global_load_dwordx4 v[92:95], v160, s[12:13] offset:3072
	s_mov_b32 s98, -1
.Lhn_it_a:
	s_add_i32 s5, s4, s74
	s_cmp_lt_i32 s5, 0x4000
	s_cselect_b32 s99, s5, s4
	s_lshl_b32 s99, s99, 13
	s_add_u32 s14, s2, s99
	s_addc_u32 s15, s3, 0
	s_lshr_b32 s100, s4, 12
	s_cmp_eq_u32 s100, s98
	s_cbranch_scc1 .Lhn_nomod_a
	s_mul_i32 s101, s100, 0x6000
	s_add_u32 s12, s6, s101
	s_addc_u32 s13, s7, 0
	s_mov_b32 s98, s100
	global_load_dwordx4 v[128:131], v160, s[12:13] offset:-4096
	global_load_dwordx4 v[132:135], v160, s[12:13] offset:-3072
	global_load_dwordx4 v[136:139], v160, s[12:13] offset:-2048
	global_load_dwordx4 v[140:143], v160, s[12:13] offset:-1024
	global_load_dwordx4 v[144:147], v160, s[12:13] offset:0
	global_load_dwordx4 v[148:151], v160, s[12:13] offset:1024
	global_load_dwordx4 v[152:155], v160, s[12:13] offset:2048
	global_load_dwordx4 v[156:159], v160, s[12:13] offset:3072
	s_add_u32 s12, s12, 0x2000
	s_addc_u32 s13, s13, 0
	global_load_dwordx4 v[96:99], v160, s[12:13] offset:-4096
	global_load_dwordx4 v[100:103], v160, s[12:13] offset:-3072
	global_load_dwordx4 v[104:107], v160, s[12:13] offset:-2048
	global_load_dwordx4 v[108:111], v160, s[12:13] offset:-1024
	global_load_dwordx4 v[112:115], v160, s[12:13] offset:0
	global_load_dwordx4 v[116:119], v160, s[12:13] offset:1024
	global_load_dwordx4 v[120:123], v160, s[12:13] offset:2048
	global_load_dwordx4 v[124:127], v160, s[12:13] offset:3072
	global_load_dwordx4 v[32:35], v160, s[14:15] offset:-4096 nt
	global_load_dwordx4 v[36:39], v160, s[14:15] offset:-3072 nt
	global_load_dwordx4 v[40:43], v160, s[14:15] offset:-2048 nt
	global_load_dwordx4 v[44:47], v160, s[14:15] offset:-1024 nt
	global_load_dwordx4 v[48:51], v160, s[14:15] offset:0 nt
	global_load_dwordx4 v[52:55], v160, s[14:15] offset:1024 nt
	global_load_dwordx4 v[56:59], v160, s[14:15] offset:2048 nt
	global_load_dwordx4 v[60:63], v160, s[14:15] offset:3072 nt
	s_waitcnt vmcnt(32)
	v_pk_mul_f32 v[168:169], v[0:1], v[0:1]
	v_pk_mul_f32 v[170:171], v[2:3], v[2:3]
	v_pk_fma_f32 v[168:169], v[4:5], v[4:5], v[168:169]
	v_pk_fma_f32 v[170:171], v[6:7], v[6:7], v[170:171]
	v_pk_fma_f32 v[168:169], v[8:9], v[8:9], v[168:169]
	v_pk_fma_f32 v[170:171], v[10:11], v[10:11], v[170:171]
	v_pk_fma_f32 v[168:169], v[12:13], v[12:13], v[168:169]
	v_pk_fma_f32 v[170:171], v[14:15], v[14:15], v[170:171]
	v_pk_fma_f32 v[168:169], v[16:17], v[16:17], v[168:169]
	v_pk_fma_f32 v[170:171], v[18:19], v[18:19], v[170:171]
	v_pk_fma_f32 v[168:169], v[20:21], v[20:21], v[168:169]
	v_pk_fma_f32 v[170:171], v[22:23], v[22:23], v[170:171]
	v_pk_fma_f32 v[168:169], v[24:25], v[24:25], v[168:169]
	v_pk_fma_f32 v[170:171], v[26:27], v[26:27], v[170:171]
	v_pk_fma_f32 v[168:169], v[28:29], v[28:29], v[168:169]
	v_pk_fma_f32 v[170:171], v[30:31], v[30:31], v[170:171]
	s_nop 0
	v_pk_add_f32 v[168:169], v[168:169], v[170:171]
	s_nop 0
	v_add_f32_e32 v168, v168, v169
	ds_bpermute_b32 v169, v162, v168
	s_waitcnt lgkmcnt(0)
	v_add_f32_e32 v168, v168, v169
	ds_bpermute_b32 v169, v163, v168
	s_waitcnt lgkmcnt(0)
	v_add_f32_e32 v168, v168, v169
	ds_bpermute_b32 v169, v164, v168
	s_waitcnt lgkmcnt(0)
	v_add_f32_e32 v168, v168, v169
	ds_bpermute_b32 v169, v165, v168
	s_waitcnt lgkmcnt(0)
	v_add_f32_e32 v168, v168, v169
	ds_bpermute_b32 v169, v166, v168
	s_waitcnt lgkmcnt(0)
; __device__ __forceinline__ void phase_norm(PP p, int l, const float* mod, int lane, int wave) {
;     ...
;         for (int j = 0; j < 8; ++j) { v[j] = xr[64 * j]; s += (v[j].x * v[j].x + v[j].y * v[j].y) + (v[j].z * v[j].z + v[j].w * v[j].w); }
;         s = wave_sum(s);
;         const float rstd = 1.f / sqrtf(s * (1.f / DM) + RMS_EPS);
;         u32x2* o8 = (u32x2*)(H + (size_t)row * DM) + lane;
; #pragma unroll
;         for (int j = 0; j < 8; ++j) { const int col = 4 * lane + 256 * j;
;             const f32x4 g4 = *(const f32x4*)(ng + col), sh = *(const f32x4*)(modl + (size_t)b * NMOD + col), sc = *(const f32x4*)(modl + (size_t)b * NMOD + DM + col);
;             const f32x4 y = v[j] * rstd * g4 * (sc + 1.f) + sh;
	v_add_f32_e32 v168, v168, v169
	ds_bpermute_b32 v169, v167, v168
	s_waitcnt lgkmcnt(0)
	v_add_f32_e32 v168, v168, v169
	v_mov_b32_e32 v169, 0x358637bd
	v_fmamk_f32 v168, v168, 0x3a000000, v169
	v_cmp_gt_f32_e32 vcc, 0xf800000, v168
	v_mul_f32_e32 v169, 0x4f800000, v168
	s_nop 0
	v_cndmask_b32_e32 v168, v168, v169, vcc
	v_sqrt_f32_e32 v169, v168
	s_nop 0
	v_add_u32_e32 v170, -1, v169
	v_fma_f32 v171, -v170, v169, v168
	v_cmp_ge_f32_e64 s[100:101], 0, v171
	v_add_u32_e32 v171, 1, v169
	s_nop 0
	v_cndmask_b32_e64 v170, v169, v170, s[100:101]
	v_fma_f32 v169, -v171, v169, v168
	v_cmp_lt_f32_e64 s[100:101], 0, v169
	s_nop 1
	v_cndmask_b32_e64 v169, v170, v171, s[100:101]
	v_mul_f32_e32 v170, 0x37800000, v169
	v_cndmask_b32_e32 v169, v169, v170, vcc
	v_mov_b32_e32 v170, 0x260
	v_cmp_class_f32_e32 vcc, v168, v170
	s_nop 1
	v_cndmask_b32_e32 v168, v169, v168, vcc
	v_div_scale_f32 v169, s[100:101], v168, v168, 1.0
	v_rcp_f32_e32 v170, v169
	s_nop 0
	v_fma_f32 v171, -v169, v170, 1.0
	v_fmac_f32_e32 v170, v171, v170
	v_div_scale_f32 v171, vcc, 1.0, v168, 1.0
	v_mul_f32_e32 v172, v171, v170
	v_fma_f32 v173, -v169, v172, v171
	v_fmac_f32_e32 v172, v173, v170
	v_fma_f32 v169, -v169, v172, v171
	s_nop 0
	v_div_fmas_f32 v169, v169, v170, v172
	v_div_fixup_f32 v172, v169, v168, 1.0
	s_waitcnt vmcnt(8)
	v_pk_add_f32 v[96:97], v[96:97], 1.0 op_sel_hi:[1,0]
	v_pk_add_f32 v[98:99], v[98:99], 1.0 op_sel_hi:[1,0]
	v_pk_add_f32 v[100:101], v[100:101], 1.0 op_sel_hi:[1,0]
	v_pk_add_f32 v[102:103], v[102:103], 1.0 op_sel_hi:[1,0]
	v_pk_add_f32 v[104:105], v[104:105], 1.0 op_sel_hi:[1,0]
	v_pk_add_f32 v[106:107], v[106:107], 1.0 op_sel_hi:[1,0]
	v_pk_add_f32 v[108:109], v[108:109], 1.0 op_sel_hi:[1,0]
	v_pk_add_f32 v[110:111], v[110:111], 1.0 op_sel_hi:[1,0]
	v_pk_add_f32 v[112:113], v[112:113], 1.0 op_sel_hi:[1,0]
	v_pk_add_f32 v[114:115], v[114:115], 1.0 op_sel_hi:[1,0]
	v_pk_add_f32 v[116:117], v[116:117], 1.0 op_sel_hi:[1,0]
	v_pk_add_f32 v[118:119], v[118:119], 1.0 op_sel_hi:[1,0]
	v_pk_add_f32 v[120:121], v[120:121], 1.0 op_sel_hi:[1,0]
	v_pk_add_f32 v[122:123], v[122:123], 1.0 op_sel_hi:[1,0]
	v_pk_add_f32 v[124:125], v[124:125], 1.0 op_sel_hi:[1,0]
	v_pk_add_f32 v[126:127], v[126:127], 1.0 op_sel_hi:[1,0]
	s_branch .Lhn_comp_a
.Lhn_nomod_a:
	global_load_dwordx4 v[32:35], v160, s[14:15] offset:-4096 nt
	global_load_dwordx4 v[36:39], v160, s[14:15] offset:-3072 nt
	global_load_dwordx4 v[40:43], v160, s[14:15] offset:-2048 nt
	global_load_dwordx4 v[44:47], v160, s[14:15] offset:-1024 nt
	global_load_dwordx4 v[48:51], v160, s[14:15] offset:0 nt
	global_load_dwordx4 v[52:55], v160, s[14:15] offset:1024 nt
	global_load_dwordx4 v[56:59], v160, s[14:15] offset:2048 nt
	global_load_dwordx4 v[60:63], v160, s[14:15] offset:3072 nt
	s_waitcnt vmcnt(16)
	v_pk_mul_f32 v[168:169], v[0:1], v[0:1]
	v_pk_mul_f32 v[170:171], v[2:3], v[2:3]
	v_pk_fma_f32 v[168:169], v[4:5], v[4:5], v[168:169]
	v_pk_fma_f32 v[170:171], v[6:7], v[6:7], v[170:171]
	v_pk_fma_f32 v[168:169], v[8:9], v[8:9], v[168:169]
	v_pk_fma_f32 v[170:171], v[10:11], v[10:11], v[170:171]
	v_pk_fma_f32 v[168:169], v[12:13], v[12:13], v[168:169]
	v_pk_fma_f32 v[170:171], v[14:15], v[14:15], v[170:171]
	v_pk_fma_f32 v[168:169], v[16:17], v[16:17], v[168:169]
	v_pk_fma_f32 v[170:171], v[18:19], v[18:19], v[170:171]
	v_pk_fma_f32 v[168:169], v[20:21], v[20:21], v[168:169]
	v_pk_fma_f32 v[170:171], v[22:23], v[22:23], v[170:171]
	v_pk_fma_f32 v[168:169], v[24:25], v[24:25], v[168:169]
	v_pk_fma_f32 v[170:171], v[26:27], v[26:27], v[170:171]
	v_pk_fma_f32 v[168:169], v[28:29], v[28:29], v[168:169]
	v_pk_fma_f32 v[170:171], v[30:31], v[30:31], v[170:171]
	s_nop 0
	v_pk_add_f32 v[168:169], v[168:169], v[170:171]
	s_nop 0
	v_add_f32_e32 v168, v168, v169
	ds_bpermute_b32 v169, v162, v168
	s_waitcnt lgkmcnt(0)
	v_add_f32_e32 v168, v168, v169
	ds_bpermute_b32 v169, v163, v168
	s_waitcnt lgkmcnt(0)
	v_add_f32_e32 v168, v168, v169
	ds_bpermute_b32 v169, v164, v168
	s_waitcnt lgkmcnt(0)
	v_add_f32_e32 v168, v168, v169
	ds_bpermute_b32 v169, v165, v168
	s_waitcnt lgkmcnt(0)
	v_add_f32_e32 v168, v168, v169
	ds_bpermute_b32 v169, v166, v168
	s_waitcnt lgkmcnt(0)
	v_add_f32_e32 v168, v168, v169
	ds_bpermute_b32 v169, v167, v168
	s_waitcnt lgkmcnt(0)
	v_add_f32_e32 v168, v168, v169
	v_mov_b32_e32 v169, 0x358637bd
	v_fmamk_f32 v168, v168, 0x3a000000, v169
	v_cmp_gt_f32_e32 vcc, 0xf800000, v168
	v_mul_f32_e32 v169, 0x4f800000, v168
	s_nop 0
	v_cndmask_b32_e32 v168, v168, v169, vcc
	v_sqrt_f32_e32 v169, v168
	s_nop 0
	v_add_u32_e32 v170, -1, v169
	v_fma_f32 v171, -v170, v169, v168
	v_cmp_ge_f32_e64 s[100:101], 0, v171
	v_add_u32_e32 v171, 1, v169
	s_nop 0
	v_cndmask_b32_e64 v170, v169, v170, s[100:101]
	v_fma_f32 v169, -v171, v169, v168
	v_cmp_lt_f32_e64 s[100:101], 0, v169
	s_nop 1
	v_cndmask_b32_e64 v169, v170, v171, s[100:101]
	v_mul_f32_e32 v170, 0x37800000, v169
	v_cndmask_b32_e32 v169, v169, v170, vcc
	v_mov_b32_e32 v170, 0x260
	v_cmp_class_f32_e32 vcc, v168, v170
	s_nop 1
	v_cndmask_b32_e32 v168, v169, v168, vcc
	v_div_scale_f32 v169, s[100:101], v168, v168, 1.0
	v_rcp_f32_e32 v170, v169
	s_nop 0
	v_fma_f32 v171, -v169, v170, 1.0
	v_fmac_f32_e32 v170, v171, v170
	v_div_scale_f32 v171, vcc, 1.0, v168, 1.0
	v_mul_f32_e32 v172, v171, v170
	v_fma_f32 v173, -v169, v172, v171
	v_fmac_f32_e32 v172, v173, v170
	v_fma_f32 v169, -v169, v172, v171
	s_nop 0
	v_div_fmas_f32 v169, v169, v170, v172
	v_div_fixup_f32 v172, v169, v168, 1.0

; __device__ __forceinline__ void phase_norm(PP p, int l, const float* mod, int lane, int wave) {
;     ...
;     for (int row = gw; row < MTOK; row += NGW) {
;         const int b = row >> 12;
;         const f32x4* xr = (const f32x4*)(xin + (size_t)row * DM) + lane;
;         f32x4 v[8]; float s = 0.f;
; #pragma unroll
;         for (int j = 0; j < 8; ++j) { v[j] = xr[64 * j]; s += (v[j].x * v[j].x + v[j].y * v[j].y) + (v[j].z * v[j].z + v[j].w * v[j].w); }
;         s = wave_sum(s);
;         const float rstd = 1.f / sqrtf(s * (1.f / DM) + RMS_EPS);
.Lhn_it_b:
	s_add_i32 s5, s4, s74
	s_cmp_lt_i32 s5, 0x4000
	s_cselect_b32 s99, s5, s4
	s_lshl_b32 s99, s99, 13
	s_add_u32 s14, s2, s99
	s_addc_u32 s15, s3, 0
	s_lshr_b32 s100, s4, 12
	s_cmp_eq_u32 s100, s98
	s_cbranch_scc1 .Lhn_nomod_b
	s_mul_i32 s101, s100, 0x6000
	s_add_u32 s12, s6, s101
	s_addc_u32 s13, s7, 0
	s_mov_b32 s98, s100
	global_load_dwordx4 v[128:131], v160, s[12:13] offset:-4096
	global_load_dwordx4 v[132:135], v160, s[12:13] offset:-3072
	global_load_dwordx4 v[136:139], v160, s[12:13] offset:-2048
	global_load_dwordx4 v[140:143], v160, s[12:13] offset:-1024
	global_load_dwordx4 v[144:147], v160, s[12:13] offset:0
	global_load_dwordx4 v[148:151], v160, s[12:13] offset:1024
	global_load_dwordx4 v[152:155], v160, s[12:13] offset:2048
	global_load_dwordx4 v[156:159], v160, s[12:13] offset:3072
	s_add_u32 s12, s12, 0x2000
	s_addc_u32 s13, s13, 0
	global_load_dwordx4 v[96:99], v160, s[12:13] offset:-4096
	global_load_dwordx4 v[100:103], v160, s[12:13] offset:-3072
	global_load_dwordx4 v[104:107], v160, s[12:13] offset:-2048
	global_load_dwordx4 v[108:111], v160, s[12:13] offset:-1024
	global_load_dwordx4 v[112:115], v160, s[12:13] offset:0
	global_load_dwordx4 v[116:119], v160, s[12:13] offset:1024
	global_load_dwordx4 v[120:123], v160, s[12:13] offset:2048
	global_load_dwordx4 v[124:127], v160, s[12:13] offset:3072
	global_load_dwordx4 v[0:3], v160, s[14:15] offset:-4096 nt
	global_load_dwordx4 v[4:7], v160, s[14:15] offset:-3072 nt
	global_load_dwordx4 v[8:11], v160, s[14:15] offset:-2048 nt
	global_load_dwordx4 v[12:15], v160, s[14:15] offset:-1024 nt
	global_load_dwordx4 v[16:19], v160, s[14:15] offset:0 nt
	global_load_dwordx4 v[20:23], v160, s[14:15] offset:1024 nt
	global_load_dwordx4 v[24:27], v160, s[14:15] offset:2048 nt
	global_load_dwordx4 v[28:31], v160, s[14:15] offset:3072 nt
	s_waitcnt vmcnt(32)
	v_pk_mul_f32 v[168:169], v[32:33], v[32:33]
	v_pk_mul_f32 v[170:171], v[34:35], v[34:35]
	v_pk_fma_f32 v[168:169], v[36:37], v[36:37], v[168:169]
	v_pk_fma_f32 v[170:171], v[38:39], v[38:39], v[170:171]
	v_pk_fma_f32 v[168:169], v[40:41], v[40:41], v[168:169]
	v_pk_fma_f32 v[170:171], v[42:43], v[42:43], v[170:171]
	v_pk_fma_f32 v[168:169], v[44:45], v[44:45], v[168:169]
	v_pk_fma_f32 v[170:171], v[46:47], v[46:47], v[170:171]
	v_pk_fma_f32 v[168:169], v[48:49], v[48:49], v[168:169]
	v_pk_fma_f32 v[170:171], v[50:51], v[50:51], v[170:171]
	v_pk_fma_f32 v[168:169], v[52:53], v[52:53], v[168:169]
	v_pk_fma_f32 v[170:171], v[54:55], v[54:55], v[170:171]
	v_pk_fma_f32 v[168:169], v[56:57], v[56:57], v[168:169]
	v_pk_fma_f32 v[170:171], v[58:59], v[58:59], v[170:171]
	v_pk_fma_f32 v[168:169], v[60:61], v[60:61], v[168:169]
	v_pk_fma_f32 v[170:171], v[62:63], v[62:63], v[170:171]
	s_nop 0
	v_pk_add_f32 v[168:169], v[168:169], v[170:171]
	s_nop 0
	v_add_f32_e32 v168, v168, v169
	ds_bpermute_b32 v169, v162, v168
	s_waitcnt lgkmcnt(0)
	v_add_f32_e32 v168, v168, v169
	ds_bpermute_b32 v169, v163, v168
	s_waitcnt lgkmcnt(0)
	v_add_f32_e32 v168, v168, v169
	ds_bpermute_b32 v169, v164, v168
	s_waitcnt lgkmcnt(0)
	v_add_f32_e32 v168, v168, v169
	ds_bpermute_b32 v169, v165, v168
	s_waitcnt lgkmcnt(0)
	v_add_f32_e32 v168, v168, v169
	ds_bpermute_b32 v169, v166, v168
	s_waitcnt lgkmcnt(0)
	v_add_f32_e32 v168, v168, v169
	ds_bpermute_b32 v169, v167, v168
	s_waitcnt lgkmcnt(0)
	v_add_f32_e32 v168, v168, v169
	v_mov_b32_e32 v169, 0x358637bd
	v_fmamk_f32 v168, v168, 0x3a000000, v169
	v_cmp_gt_f32_e32 vcc, 0xf800000, v168
	v_mul_f32_e32 v169, 0x4f800000, v168
	s_nop 0
	v_cndmask_b32_e32 v168, v168, v169, vcc
	v_sqrt_f32_e32 v169, v168
	s_nop 0
	v_add_u32_e32 v170, -1, v169
	v_fma_f32 v171, -v170, v169, v168
	v_cmp_ge_f32_e64 s[100:101], 0, v171
	v_add_u32_e32 v171, 1, v169
	s_nop 0
	v_cndmask_b32_e64 v170, v169, v170, s[100:101]
	v_fma_f32 v169, -v171, v169, v168
	v_cmp_lt_f32_e64 s[100:101], 0, v169
	s_nop 1
	v_cndmask_b32_e64 v169, v170, v171, s[100:101]
	v_mul_f32_e32 v170, 0x37800000, v169
	v_cndmask_b32_e32 v169, v169, v170, vcc
	v_mov_b32_e32 v170, 0x260
	v_cmp_class_f32_e32 vcc, v168, v170
	s_nop 1
	v_cndmask_b32_e32 v168, v169, v168, vcc
	v_div_scale_f32 v169, s[100:101], v168, v168, 1.0
	v_rcp_f32_e32 v170, v169
	s_nop 0
	v_fma_f32 v171, -v169, v170, 1.0
	v_fmac_f32_e32 v170, v171, v170
	v_div_scale_f32 v171, vcc, 1.0, v168, 1.0
	v_mul_f32_e32 v172, v171, v170
	v_fma_f32 v173, -v169, v172, v171
	v_fmac_f32_e32 v172, v173, v170
	v_fma_f32 v169, -v169, v172, v171
	s_nop 0
	v_div_fmas_f32 v169, v169, v170, v172
	v_div_fixup_f32 v172, v169, v168, 1.0
	s_waitcnt vmcnt(8)
	v_pk_add_f32 v[96:97], v[96:97], 1.0 op_sel_hi:[1,0]
	v_pk_add_f32 v[98:99], v[98:99], 1.0 op_sel_hi:[1,0]
	v_pk_add_f32 v[100:101], v[100:101], 1.0 op_sel_hi:[1,0]
	v_pk_add_f32 v[102:103], v[102:103], 1.0 op_sel_hi:[1,0]
	v_pk_add_f32 v[104:105], v[104:105], 1.0 op_sel_hi:[1,0]
	v_pk_add_f32 v[106:107], v[106:107], 1.0 op_sel_hi:[1,0]
	v_pk_add_f32 v[108:109], v[108:109], 1.0 op_sel_hi:[1,0]
	v_pk_add_f32 v[110:111], v[110:111], 1.0 op_sel_hi:[1,0]
	v_pk_add_f32 v[112:113], v[112:113], 1.0 op_sel_hi:[1,0]
	v_pk_add_f32 v[114:115], v[114:115], 1.0 op_sel_hi:[1,0]
	v_pk_add_f32 v[116:117], v[116:117], 1.0 op_sel_hi:[1,0]
	v_pk_add_f32 v[118:119], v[118:119], 1.0 op_sel_hi:[1,0]
	v_pk_add_f32 v[120:121], v[120:121], 1.0 op_sel_hi:[1,0]
	v_pk_add_f32 v[122:123], v[122:123], 1.0 op_sel_hi:[1,0]
	v_pk_add_f32 v[124:125], v[124:125], 1.0 op_sel_hi:[1,0]
	v_pk_add_f32 v[126:127], v[126:127], 1.0 op_sel_hi:[1,0]
	s_branch .Lhn_comp_b
; __device__ __forceinline__ void phase_norm(PP p, int l, const float* mod, int lane, int wave) {
;     ...
;     for (int row = gw; row < MTOK; row += NGW) {
;         const int b = row >> 12;
;         const f32x4* xr = (const f32x4*)(xin + (size_t)row * DM) + lane;
;         f32x4 v[8]; float s = 0.f;
; #pragma unroll
;         for (int j = 0; j < 8; ++j) { v[j] = xr[64 * j]; s += (v[j].x * v[j].x + v[j].y * v[j].y) + (v[j].z * v[j].z + v[j].w * v[j].w); }
;         s = wave_sum(s);
;         const float rstd = 1.f / sqrtf(s * (1.f / DM) + RMS_EPS);
.Lhn_nomod_b:
	global_load_dwordx4 v[0:3], v160, s[14:15] offset:-4096 nt
	global_load_dwordx4 v[4:7], v160, s[14:15] offset:-3072 nt
	global_load_dwordx4 v[8:11], v160, s[14:15] offset:-2048 nt
	global_load_dwordx4 v[12:15], v160, s[14:15] offset:-1024 nt
	global_load_dwordx4 v[16:19], v160, s[14:15] offset:0 nt
	global_load_dwordx4 v[20:23], v160, s[14:15] offset:1024 nt
	global_load_dwordx4 v[24:27], v160, s[14:15] offset:2048 nt
	global_load_dwordx4 v[28:31], v160, s[14:15] offset:3072 nt
	s_waitcnt vmcnt(16)
	v_pk_mul_f32 v[168:169], v[32:33], v[32:33]
	v_pk_mul_f32 v[170:171], v[34:35], v[34:35]
	v_pk_fma_f32 v[168:169], v[36:37], v[36:37], v[168:169]
	v_pk_fma_f32 v[170:171], v[38:39], v[38:39], v[170:171]
	v_pk_fma_f32 v[168:169], v[40:41], v[40:41], v[168:169]
	v_pk_fma_f32 v[170:171], v[42:43], v[42:43], v[170:171]
	v_pk_fma_f32 v[168:169], v[44:45], v[44:45], v[168:169]
	v_pk_fma_f32 v[170:171], v[46:47], v[46:47], v[170:171]
	v_pk_fma_f32 v[168:169], v[48:49], v[48:49], v[168:169]
	v_pk_fma_f32 v[170:171], v[50:51], v[50:51], v[170:171]
	v_pk_fma_f32 v[168:169], v[52:53], v[52:53], v[168:169]
	v_pk_fma_f32 v[170:171], v[54:55], v[54:55], v[170:171]
	v_pk_fma_f32 v[168:169], v[56:57], v[56:57], v[168:169]
	v_pk_fma_f32 v[170:171], v[58:59], v[58:59], v[170:171]
	v_pk_fma_f32 v[168:169], v[60:61], v[60:61], v[168:169]
	v_pk_fma_f32 v[170:171], v[62:63], v[62:63], v[170:171]
	s_nop 0
	v_pk_add_f32 v[168:169], v[168:169], v[170:171]
	s_nop 0
	v_add_f32_e32 v168, v168, v169
	ds_bpermute_b32 v169, v162, v168
	s_waitcnt lgkmcnt(0)
	v_add_f32_e32 v168, v168, v169
	ds_bpermute_b32 v169, v163, v168
	s_waitcnt lgkmcnt(0)
	v_add_f32_e32 v168, v168, v169
	ds_bpermute_b32 v169, v164, v168
	s_waitcnt lgkmcnt(0)
	v_add_f32_e32 v168, v168, v169
	ds_bpermute_b32 v169, v165, v168
	s_waitcnt lgkmcnt(0)
	v_add_f32_e32 v168, v168, v169
	ds_bpermute_b32 v169, v166, v168
	s_waitcnt lgkmcnt(0)
	v_add_f32_e32 v168, v168, v169
	ds_bpermute_b32 v169, v167, v168
	s_waitcnt lgkmcnt(0)
	v_add_f32_e32 v168, v168, v169
	v_mov_b32_e32 v169, 0x358637bd
	v_fmamk_f32 v168, v168, 0x3a000000, v169
	v_cmp_gt_f32_e32 vcc, 0xf800000, v168
	v_mul_f32_e32 v169, 0x4f800000, v168
	s_nop 0
	v_cndmask_b32_e32 v168, v168, v169, vcc
	v_sqrt_f32_e32 v169, v168
	s_nop 0
	v_add_u32_e32 v170, -1, v169
	v_fma_f32 v171, -v170, v169, v168
	v_cmp_ge_f32_e64 s[100:101], 0, v171
	v_add_u32_e32 v171, 1, v169
	s_nop 0
	v_cndmask_b32_e64 v170, v169, v170, s[100:101]
	v_fma_f32 v169, -v171, v169, v168
	v_cmp_lt_f32_e64 s[100:101], 0, v169
	s_nop 1
	v_cndmask_b32_e64 v169, v170, v171, s[100:101]
	v_mul_f32_e32 v170, 0x37800000, v169
	v_cndmask_b32_e32 v169, v169, v170, vcc
	v_mov_b32_e32 v170, 0x260
	v_cmp_class_f32_e32 vcc, v168, v170
	s_nop 1
	v_cndmask_b32_e32 v168, v169, v168, vcc
	v_div_scale_f32 v169, s[100:101], v168, v168, 1.0
	v_rcp_f32_e32 v170, v169
	s_nop 0
	v_fma_f32 v171, -v169, v170, 1.0
	v_fmac_f32_e32 v170, v171, v170
	v_div_scale_f32 v171, vcc, 1.0, v168, 1.0
	v_mul_f32_e32 v172, v171, v170
	v_fma_f32 v173, -v169, v172, v171
	v_fmac_f32_e32 v172, v173, v170
	v_fma_f32 v169, -v169, v172, v171
	s_nop 0
	v_div_fmas_f32 v169, v169, v170, v172
	v_div_fixup_f32 v172, v169, v168, 1.0

; __device__ __forceinline__ void phase_final(PP p, int lane, int wave) {
;     const int gw = blockIdx.x * 8 + wave, NGW = gridDim.x * 8;
;     for (int row = gw; row < MTOK; row += NGW) {
;         f32x4* xr = (f32x4*)(p->out + (size_t)row * DM) + lane;
;         f32x4 v[8]; float s = 0.f;
; #pragma unroll
;         for (int j = 0; j < 8; ++j) { v[j] = xr[64 * j]; s += (v[j].x * v[j].x + v[j].y * v[j].y) + (v[j].z * v[j].z + v[j].w * v[j].w); }
;         s = wave_sum(s);
;         const float rstd = 1.f / sqrtf(s * (1.f / DM) + RMS_EPS);
; #pragma unroll
;         for (int j = 0; j < 8; ++j) { const f32x4 g4 = *(const f32x4*)(p->final_g + 4 * lane + 256 * j); xr[64 * j] = v[j] * rstd * g4; }
.LBB0_658:
	s_add_i32 s2, s80, s81
	s_mov_b32 s0, 0
	s_cmpk_gt_i32 s2, 0x3fff
	s_cbranch_scc1 .LBB0_661
	s_mov_b32 s4, s2
	s_load_dwordx4 s[8:11], s[68:69], 0x78
	v_lshlrev_b32_e32 v160, 4, v239
	v_lshlrev_b32_e32 v161, 3, v239
	v_xor_b32_e32 v162, 1, v239
	v_xor_b32_e32 v163, 2, v239
	v_xor_b32_e32 v164, 4, v239
	v_xor_b32_e32 v165, 8, v239
	v_xor_b32_e32 v166, 16, v239
	v_xor_b32_e32 v167, 32, v239
	v_lshlrev_b32_e32 v162, 2, v162
	v_lshlrev_b32_e32 v163, 2, v163
	v_lshlrev_b32_e32 v164, 2, v164
	v_lshlrev_b32_e32 v165, 2, v165
	v_lshlrev_b32_e32 v166, 2, v166
	v_lshlrev_b32_e32 v167, 2, v167
	s_waitcnt lgkmcnt(0)
	s_add_u32 s2, s10, 0x1000
	s_addc_u32 s3, s11, 0
	s_add_u32 s12, s8, 0x1000
	s_addc_u32 s13, s9, 0
	s_lshl_b32 s5, s4, 13
	s_add_u32 s14, s2, s5
	s_addc_u32 s15, s3, 0
	global_load_dwordx4 v[64:67], v160, s[12:13] offset:-4096
	global_load_dwordx4 v[68:71], v160, s[12:13] offset:-3072
	global_load_dwordx4 v[72:75], v160, s[12:13] offset:-2048
	global_load_dwordx4 v[76:79], v160, s[12:13] offset:-1024
	global_load_dwordx4 v[80:83], v160, s[12:13] offset:0
	global_load_dwordx4 v[84:87], v160, s[12:13] offset:1024
	global_load_dwordx4 v[88:91], v160, s[12:13] offset:2048
	global_load_dwordx4 v[92:95], v160, s[12:13] offset:3072
	global_load_dwordx4 v[0:3], v160, s[14:15] offset:-4096 nt
	global_load_dwordx4 v[4:7], v160, s[14:15] offset:-3072 nt
	global_load_dwordx4 v[8:11], v160, s[14:15] offset:-2048 nt
	global_load_dwordx4 v[12:15], v160, s[14:15] offset:-1024 nt
	global_load_dwordx4 v[16:19], v160, s[14:15] offset:0 nt
	global_load_dwordx4 v[20:23], v160, s[14:15] offset:1024 nt
	global_load_dwordx4 v[24:27], v160, s[14:15] offset:2048 nt
	global_load_dwordx4 v[28:31], v160, s[14:15] offset:3072 nt
.Lhf_it_f:
	s_add_i32 s5, s4, s74
	s_cmp_lt_i32 s5, 0x4000
	s_cselect_b32 s99, s5, s4
	s_lshl_b32 s99, s99, 13
	s_add_u32 s14, s2, s99
	s_addc_u32 s15, s3, 0
	global_load_dwordx4 v[32:35], v160, s[14:15] offset:-4096 nt
	global_load_dwordx4 v[36:39], v160, s[14:15] offset:-3072 nt
	global_load_dwordx4 v[40:43], v160, s[14:15] offset:-2048 nt
	global_load_dwordx4 v[44:47], v160, s[14:15] offset:-1024 nt
	global_load_dwordx4 v[48:51], v160, s[14:15] offset:0 nt
	global_load_dwordx4 v[52:55], v160, s[14:15] offset:1024 nt
	global_load_dwordx4 v[56:59], v160, s[14:15] offset:2048 nt
	global_load_dwordx4 v[60:63], v160, s[14:15] offset:3072 nt
	s_waitcnt vmcnt(8)
	v_pk_mul_f32 v[168:169], v[0:1], v[0:1]
	v_pk_mul_f32 v[170:171], v[2:3], v[2:3]
	v_pk_fma_f32 v[168:169], v[4:5], v[4:5], v[168:169]
	v_pk_fma_f32 v[170:171], v[6:7], v[6:7], v[170:171]
	v_pk_fma_f32 v[168:169], v[8:9], v[8:9], v[168:169]
	v_pk_fma_f32 v[170:171], v[10:11], v[10:11], v[170:171]
	v_pk_fma_f32 v[168:169], v[12:13], v[12:13], v[168:169]
	v_pk_fma_f32 v[170:171], v[14:15], v[14:15], v[170:171]
	v_pk_fma_f32 v[168:169], v[16:17], v[16:17], v[168:169]
	v_pk_fma_f32 v[170:171], v[18:19], v[18:19], v[170:171]
	v_pk_fma_f32 v[168:169], v[20:21], v[20:21], v[168:169]
	v_pk_fma_f32 v[170:171], v[22:23], v[22:23], v[170:171]
	v_pk_fma_f32 v[168:169], v[24:25], v[24:25], v[168:169]
	v_pk_fma_f32 v[170:171], v[26:27], v[26:27], v[170:171]
	v_pk_fma_f32 v[168:169], v[28:29], v[28:29], v[168:169]
	v_pk_fma_f32 v[170:171], v[30:31], v[30:31], v[170:171]
	s_nop 0
	v_pk_add_f32 v[168:169], v[168:169], v[170:171]
	s_nop 0
	v_add_f32_e32 v168, v168, v169
	ds_bpermute_b32 v169, v162, v168
	s_waitcnt lgkmcnt(0)
	v_add_f32_e32 v168, v168, v169
	ds_bpermute_b32 v169, v163, v168
	s_waitcnt lgkmcnt(0)
	v_add_f32_e32 v168, v168, v169
	ds_bpermute_b32 v169, v164, v168
	s_waitcnt lgkmcnt(0)
	v_add_f32_e32 v168, v168, v169
	ds_bpermute_b32 v169, v165, v168
	s_waitcnt lgkmcnt(0)
	v_add_f32_e32 v168, v168, v169
	ds_bpermute_b32 v169, v166, v168
	s_waitcnt lgkmcnt(0)
	v_add_f32_e32 v168, v168, v169
	ds_bpermute_b32 v169, v167, v168
	s_waitcnt lgkmcnt(0)
	v_add_f32_e32 v168, v168, v169
	v_mov_b32_e32 v169, 0x358637bd
	v_fmamk_f32 v168, v168, 0x3a000000, v169
	v_cmp_gt_f32_e32 vcc, 0xf800000, v168
	v_mul_f32_e32 v169, 0x4f800000, v168
	s_nop 0
	v_cndmask_b32_e32 v168, v168, v169, vcc
	v_sqrt_f32_e32 v169, v168
	s_nop 0
	v_add_u32_e32 v170, -1, v169
	v_fma_f32 v171, -v170, v169, v168
	v_cmp_ge_f32_e64 s[100:101], 0, v171
	v_add_u32_e32 v171, 1, v169
	s_nop 0
	v_cndmask_b32_e64 v170, v169, v170, s[100:101]
	v_fma_f32 v169, -v171, v169, v168
	v_cmp_lt_f32_e64 s[100:101], 0, v169
	s_nop 1
	v_cndmask_b32_e64 v169, v170, v171, s[100:101]
	v_mul_f32_e32 v170, 0x37800000, v169
	v_cndmask_b32_e32 v169, v169, v170, vcc
	v_mov_b32_e32 v170, 0x260
	v_cmp_class_f32_e32 vcc, v168, v170
	s_nop 1
	v_cndmask_b32_e32 v168, v169, v168, vcc
	v_div_scale_f32 v169, s[100:101], v168, v168, 1.0
	v_rcp_f32_e32 v170, v169
	s_nop 0
	v_fma_f32 v171, -v169, v170, 1.0
	v_fmac_f32_e32 v170, v171, v170
	v_div_scale_f32 v171, vcc, 1.0, v168, 1.0
	v_mul_f32_e32 v172, v171, v170
	v_fma_f32 v173, -v169, v172, v171
	v_fmac_f32_e32 v172, v173, v170
	v_fma_f32 v169, -v169, v172, v171
	s_nop 0
	v_div_fmas_f32 v169, v169, v170, v172
	v_div_fixup_f32 v172, v169, v168, 1.0
	s_lshl_b32 s101, s4, 13
	s_add_u32 s12, s2, s101
	s_addc_u32 s13, s3, 0
	v_pk_mul_f32 v[0:1], v[0:1], v[172:173] op_sel_hi:[1,0]
	v_pk_mul_f32 v[2:3], v[2:3], v[172:173] op_sel_hi:[1,0]
	v_pk_mul_f32 v[0:1], v[64:65], v[0:1]
	v_pk_mul_f32 v[2:3], v[66:67], v[2:3]
	global_store_dwordx4 v160, v[0:3], s[12:13] offset:-4096 nt
	v_pk_mul_f32 v[4:5], v[4:5], v[172:173] op_sel_hi:[1,0]
	v_pk_mul_f32 v[6:7], v[6:7], v[172:173] op_sel_hi:[1,0]
	v_pk_mul_f32 v[4:5], v[68:69], v[4:5]
	v_pk_mul_f32 v[6:7], v[70:71], v[6:7]
	global_store_dwordx4 v160, v[4:7], s[12:13] offset:-3072 nt
; __device__ __forceinline__ void phase_final(PP p, int lane, int wave) {
;     ...
;     for (int row = gw; row < MTOK; row += NGW) {
;         f32x4* xr = (f32x4*)(p->out + (size_t)row * DM) + lane;
;         f32x4 v[8]; float s = 0.f;
; #pragma unroll
;         for (int j = 0; j < 8; ++j) { v[j] = xr[64 * j]; s += (v[j].x * v[j].x + v[j].y * v[j].y) + (v[j].z * v[j].z + v[j].w * v[j].w); }
;         s = wave_sum(s);
;         const float rstd = 1.f / sqrtf(s * (1.f / DM) + RMS_EPS);
; #pragma unroll
;         for (int j = 0; j < 8; ++j) { const f32x4 g4 = *(const f32x4*)(p->final_g + 4 * lane + 256 * j); xr[64 * j] = v[j] * rstd * g4; }
	v_pk_mul_f32 v[8:9], v[8:9], v[172:173] op_sel_hi:[1,0]
	v_pk_mul_f32 v[10:11], v[10:11], v[172:173] op_sel_hi:[1,0]
	v_pk_mul_f32 v[8:9], v[72:73], v[8:9]
	v_pk_mul_f32 v[10:11], v[74:75], v[10:11]
	global_store_dwordx4 v160, v[8:11], s[12:13] offset:-2048 nt
	v_pk_mul_f32 v[12:13], v[12:13], v[172:173] op_sel_hi:[1,0]
	v_pk_mul_f32 v[14:15], v[14:15], v[172:173] op_sel_hi:[1,0]
	v_pk_mul_f32 v[12:13], v[76:77], v[12:13]
	v_pk_mul_f32 v[14:15], v[78:79], v[14:15]
	global_store_dwordx4 v160, v[12:15], s[12:13] offset:-1024 nt
	v_pk_mul_f32 v[16:17], v[16:17], v[172:173] op_sel_hi:[1,0]
	v_pk_mul_f32 v[18:19], v[18:19], v[172:173] op_sel_hi:[1,0]
	v_pk_mul_f32 v[16:17], v[80:81], v[16:17]
	v_pk_mul_f32 v[18:19], v[82:83], v[18:19]
	global_store_dwordx4 v160, v[16:19], s[12:13] offset:0 nt
	v_pk_mul_f32 v[20:21], v[20:21], v[172:173] op_sel_hi:[1,0]
	v_pk_mul_f32 v[22:23], v[22:23], v[172:173] op_sel_hi:[1,0]
	v_pk_mul_f32 v[20:21], v[84:85], v[20:21]
	v_pk_mul_f32 v[22:23], v[86:87], v[22:23]
	global_store_dwordx4 v160, v[20:23], s[12:13] offset:1024 nt
	v_pk_mul_f32 v[24:25], v[24:25], v[172:173] op_sel_hi:[1,0]
	v_pk_mul_f32 v[26:27], v[26:27], v[172:173] op_sel_hi:[1,0]
	v_pk_mul_f32 v[24:25], v[88:89], v[24:25]
	v_pk_mul_f32 v[26:27], v[90:91], v[26:27]
	global_store_dwordx4 v160, v[24:27], s[12:13] offset:2048 nt
	v_pk_mul_f32 v[28:29], v[28:29], v[172:173] op_sel_hi:[1,0]
	v_pk_mul_f32 v[30:31], v[30:31], v[172:173] op_sel_hi:[1,0]
	v_pk_mul_f32 v[28:29], v[92:93], v[28:29]
	v_pk_mul_f32 v[30:31], v[94:95], v[30:31]
	global_store_dwordx4 v160, v[28:31], s[12:13] offset:3072 nt
	s_mov_b32 s4, s5
	s_cmp_lt_i32 s4, 0x4000
	s_cbranch_scc0 .Lhf_done
.Lhf_it_b:
	s_add_i32 s5, s4, s74
	s_cmp_lt_i32 s5, 0x4000
	s_cselect_b32 s99, s5, s4
	s_lshl_b32 s99, s99, 13
	s_add_u32 s14, s2, s99
	s_addc_u32 s15, s3, 0
	global_load_dwordx4 v[0:3], v160, s[14:15] offset:-4096 nt
	global_load_dwordx4 v[4:7], v160, s[14:15] offset:-3072 nt
	global_load_dwordx4 v[8:11], v160, s[14:15] offset:-2048 nt
	global_load_dwordx4 v[12:15], v160, s[14:15] offset:-1024 nt
	global_load_dwordx4 v[16:19], v160, s[14:15] offset:0 nt
	global_load_dwordx4 v[20:23], v160, s[14:15] offset:1024 nt
	global_load_dwordx4 v[24:27], v160, s[14:15] offset:2048 nt
	global_load_dwordx4 v[28:31], v160, s[14:15] offset:3072 nt
	s_waitcnt vmcnt(16)
	v_pk_mul_f32 v[168:169], v[32:33], v[32:33]
	v_pk_mul_f32 v[170:171], v[34:35], v[34:35]
	v_pk_fma_f32 v[168:169], v[36:37], v[36:37], v[168:169]
	v_pk_fma_f32 v[170:171], v[38:39], v[38:39], v[170:171]
	v_pk_fma_f32 v[168:169], v[40:41], v[40:41], v[168:169]
	v_pk_fma_f32 v[170:171], v[42:43], v[42:43], v[170:171]
	v_pk_fma_f32 v[168:169], v[44:45], v[44:45], v[168:169]
	v_pk_fma_f32 v[170:171], v[46:47], v[46:47], v[170:171]
	v_pk_fma_f32 v[168:169], v[48:49], v[48:49], v[168:169]
	v_pk_fma_f32 v[170:171], v[50:51], v[50:51], v[170:171]
	v_pk_fma_f32 v[168:169], v[52:53], v[52:53], v[168:169]
	v_pk_fma_f32 v[170:171], v[54:55], v[54:55], v[170:171]
	v_pk_fma_f32 v[168:169], v[56:57], v[56:57], v[168:169]
	v_pk_fma_f32 v[170:171], v[58:59], v[58:59], v[170:171]
	v_pk_fma_f32 v[168:169], v[60:61], v[60:61], v[168:169]
	v_pk_fma_f32 v[170:171], v[62:63], v[62:63], v[170:171]
	s_nop 0
	v_pk_add_f32 v[168:169], v[168:169], v[170:171]
	s_nop 0
	v_add_f32_e32 v168, v168, v169
	ds_bpermute_b32 v169, v162, v168
	s_waitcnt lgkmcnt(0)
	v_add_f32_e32 v168, v168, v169
	ds_bpermute_b32 v169, v163, v168
	s_waitcnt lgkmcnt(0)
	v_add_f32_e32 v168, v168, v169
	ds_bpermute_b32 v169, v164, v168
	s_waitcnt lgkmcnt(0)
	v_add_f32_e32 v168, v168, v169
	ds_bpermute_b32 v169, v165, v168
	s_waitcnt lgkmcnt(0)
	v_add_f32_e32 v168, v168, v169
	ds_bpermute_b32 v169, v166, v168
	s_waitcnt lgkmcnt(0)
	v_add_f32_e32 v168, v168, v169
	ds_bpermute_b32 v169, v167, v168
	s_waitcnt lgkmcnt(0)
	v_add_f32_e32 v168, v168, v169
	v_mov_b32_e32 v169, 0x358637bd
	v_fmamk_f32 v168, v168, 0x3a000000, v169
	v_cmp_gt_f32_e32 vcc, 0xf800000, v168
	v_mul_f32_e32 v169, 0x4f800000, v168
	s_nop 0
	v_cndmask_b32_e32 v168, v168, v169, vcc
	v_sqrt_f32_e32 v169, v168
	s_nop 0
	v_add_u32_e32 v170, -1, v169
	v_fma_f32 v171, -v170, v169, v168
	v_cmp_ge_f32_e64 s[100:101], 0, v171
	v_add_u32_e32 v171, 1, v169
	s_nop 0
	v_cndmask_b32_e64 v170, v169, v170, s[100:101]
	v_fma_f32 v169, -v171, v169, v168
	v_cmp_lt_f32_e64 s[100:101], 0, v169
	s_nop 1
	v_cndmask_b32_e64 v169, v170, v171, s[100:101]
	v_mul_f32_e32 v170, 0x37800000, v169
	v_cndmask_b32_e32 v169, v169, v170, vcc
	v_mov_b32_e32 v170, 0x260
	v_cmp_class_f32_e32 vcc, v168, v170
	s_nop 1
	v_cndmask_b32_e32 v168, v169, v168, vcc
	v_div_scale_f32 v169, s[100:101], v168, v168, 1.0
	v_rcp_f32_e32 v170, v169
	s_nop 0
	v_fma_f32 v171, -v169, v170, 1.0
	v_fmac_f32_e32 v170, v171, v170
	v_div_scale_f32 v171, vcc, 1.0, v168, 1.0
	v_mul_f32_e32 v172, v171, v170
	v_fma_f32 v173, -v169, v172, v171
	v_fmac_f32_e32 v172, v173, v170
	v_fma_f32 v169, -v169, v172, v171
	s_nop 0
	v_div_fmas_f32 v169, v169, v170, v172
	v_div_fixup_f32 v172, v169, v168, 1.0
	s_lshl_b32 s101, s4, 13
	s_add_u32 s12, s2, s101
	s_addc_u32 s13, s3, 0
	v_pk_mul_f32 v[32:33], v[32:33], v[172:173] op_sel_hi:[1,0]
	v_pk_mul_f32 v[34:35], v[34:35], v[172:173] op_sel_hi:[1,0]
	v_pk_mul_f32 v[32:33], v[64:65], v[32:33]
	v_pk_mul_f32 v[34:35], v[66:67], v[34:35]
	global_store_dwordx4 v160, v[32:35], s[12:13] offset:-4096 nt
	v_pk_mul_f32 v[36:37], v[36:37], v[172:173] op_sel_hi:[1,0]
	v_pk_mul_f32 v[38:39], v[38:39], v[172:173] op_sel_hi:[1,0]
	v_pk_mul_f32 v[36:37], v[68:69], v[36:37]
	v_pk_mul_f32 v[38:39], v[70:71], v[38:39]
	global_store_dwordx4 v160, v[36:39], s[12:13] offset:-3072 nt
; __device__ __forceinline__ void phase_final(PP p, int lane, int wave) {
;     ...
;         for (int j = 0; j < 8; ++j) { const f32x4 g4 = *(const f32x4*)(p->final_g + 4 * lane + 256 * j); xr[64 * j] = v[j] * rstd * g4; }
	v_pk_mul_f32 v[40:41], v[40:41], v[172:173] op_sel_hi:[1,0]
	v_pk_mul_f32 v[42:43], v[42:43], v[172:173] op_sel_hi:[1,0]
	v_pk_mul_f32 v[40:41], v[72:73], v[40:41]
	v_pk_mul_f32 v[42:43], v[74:75], v[42:43]
	global_store_dwordx4 v160, v[40:43], s[12:13] offset:-2048 nt
	v_pk_mul_f32 v[44:45], v[44:45], v[172:173] op_sel_hi:[1,0]
	v_pk_mul_f32 v[46:47], v[46:47], v[172:173] op_sel_hi:[1,0]
	v_pk_mul_f32 v[44:45], v[76:77], v[44:45]
	v_pk_mul_f32 v[46:47], v[78:79], v[46:47]
	global_store_dwordx4 v160, v[44:47], s[12:13] offset:-1024 nt
	v_pk_mul_f32 v[48:49], v[48:49], v[172:173] op_sel_hi:[1,0]
	v_pk_mul_f32 v[50:51], v[50:51], v[172:173] op_sel_hi:[1,0]
	v_pk_mul_f32 v[48:49], v[80:81], v[48:49]
	v_pk_mul_f32 v[50:51], v[82:83], v[50:51]
	global_store_dwordx4 v160, v[48:51], s[12:13] offset:0 nt
	v_pk_mul_f32 v[52:53], v[52:53], v[172:173] op_sel_hi:[1,0]
	v_pk_mul_f32 v[54:55], v[54:55], v[172:173] op_sel_hi:[1,0]
	v_pk_mul_f32 v[52:53], v[84:85], v[52:53]
	v_pk_mul_f32 v[54:55], v[86:87], v[54:55]
	global_store_dwordx4 v160, v[52:55], s[12:13] offset:1024 nt
	v_pk_mul_f32 v[56:57], v[56:57], v[172:173] op_sel_hi:[1,0]
	v_pk_mul_f32 v[58:59], v[58:59], v[172:173] op_sel_hi:[1,0]
	v_pk_mul_f32 v[56:57], v[88:89], v[56:57]
	v_pk_mul_f32 v[58:59], v[90:91], v[58:59]
	global_store_dwordx4 v160, v[56:59], s[12:13] offset:2048 nt
	v_pk_mul_f32 v[60:61], v[60:61], v[172:173] op_sel_hi:[1,0]
	v_pk_mul_f32 v[62:63], v[62:63], v[172:173] op_sel_hi:[1,0]
	v_pk_mul_f32 v[60:61], v[92:93], v[60:61]
	v_pk_mul_f32 v[62:63], v[94:95], v[62:63]
	global_store_dwordx4 v160, v[60:63], s[12:13] offset:3072 nt
	s_mov_b32 s4, s5
	s_cmp_lt_i32 s4, 0x4000
	s_cbranch_scc0 .Lhf_done
; __device__ __forceinline__ void phase_final(PP p, int lane, int wave) {
;     ...
;     for (int row = gw; row < MTOK; row += NGW) {
;         f32x4* xr = (f32x4*)(p->out + (size_t)row * DM) + lane;
;         f32x4 v[8]; float s = 0.f;
; #pragma unroll
;         for (int j = 0; j < 8; ++j) { v[j] = xr[64 * j]; s += (v[j].x * v[j].x + v[j].y * v[j].y) + (v[j].z * v[j].z + v[j].w * v[j].w); }
;         s = wave_sum(s);
;         const float rstd = 1.f / sqrtf(s * (1.f / DM) + RMS_EPS);
; #pragma unroll
;         for (int j = 0; j < 8; ++j) { const f32x4 g4 = *(const f32x4*)(p->final_g + 4 * lane + 256 * j); xr[64 * j] = v[j] * rstd * g4; }
.Lhf_it_a:
	s_add_i32 s5, s4, s74
	s_cmp_lt_i32 s5, 0x4000
	s_cselect_b32 s99, s5, s4
	s_lshl_b32 s99, s99, 13
	s_add_u32 s14, s2, s99
	s_addc_u32 s15, s3, 0
	global_load_dwordx4 v[32:35], v160, s[14:15] offset:-4096 nt
	global_load_dwordx4 v[36:39], v160, s[14:15] offset:-3072 nt
	global_load_dwordx4 v[40:43], v160, s[14:15] offset:-2048 nt
	global_load_dwordx4 v[44:47], v160, s[14:15] offset:-1024 nt
	global_load_dwordx4 v[48:51], v160, s[14:15] offset:0 nt
	global_load_dwordx4 v[52:55], v160, s[14:15] offset:1024 nt
	global_load_dwordx4 v[56:59], v160, s[14:15] offset:2048 nt
	global_load_dwordx4 v[60:63], v160, s[14:15] offset:3072 nt
	s_waitcnt vmcnt(16)
	v_pk_mul_f32 v[168:169], v[0:1], v[0:1]
	v_pk_mul_f32 v[170:171], v[2:3], v[2:3]
	v_pk_fma_f32 v[168:169], v[4:5], v[4:5], v[168:169]
	v_pk_fma_f32 v[170:171], v[6:7], v[6:7], v[170:171]
	v_pk_fma_f32 v[168:169], v[8:9], v[8:9], v[168:169]
	v_pk_fma_f32 v[170:171], v[10:11], v[10:11], v[170:171]
	v_pk_fma_f32 v[168:169], v[12:13], v[12:13], v[168:169]
	v_pk_fma_f32 v[170:171], v[14:15], v[14:15], v[170:171]
	v_pk_fma_f32 v[168:169], v[16:17], v[16:17], v[168:169]
	v_pk_fma_f32 v[170:171], v[18:19], v[18:19], v[170:171]
	v_pk_fma_f32 v[168:169], v[20:21], v[20:21], v[168:169]
	v_pk_fma_f32 v[170:171], v[22:23], v[22:23], v[170:171]
	v_pk_fma_f32 v[168:169], v[24:25], v[24:25], v[168:169]
	v_pk_fma_f32 v[170:171], v[26:27], v[26:27], v[170:171]
	v_pk_fma_f32 v[168:169], v[28:29], v[28:29], v[168:169]
	v_pk_fma_f32 v[170:171], v[30:31], v[30:31], v[170:171]
	s_nop 0
	v_pk_add_f32 v[168:169], v[168:169], v[170:171]
	s_nop 0
	v_add_f32_e32 v168, v168, v169
	ds_bpermute_b32 v169, v162, v168
	s_waitcnt lgkmcnt(0)
	v_add_f32_e32 v168, v168, v169
	ds_bpermute_b32 v169, v163, v168
	s_waitcnt lgkmcnt(0)
	v_add_f32_e32 v168, v168, v169
	ds_bpermute_b32 v169, v164, v168
	s_waitcnt lgkmcnt(0)
	v_add_f32_e32 v168, v168, v169
	ds_bpermute_b32 v169, v165, v168
	s_waitcnt lgkmcnt(0)
	v_add_f32_e32 v168, v168, v169
	ds_bpermute_b32 v169, v166, v168
	s_waitcnt lgkmcnt(0)
	v_add_f32_e32 v168, v168, v169
	ds_bpermute_b32 v169, v167, v168
	s_waitcnt lgkmcnt(0)
	v_add_f32_e32 v168, v168, v169
	v_mov_b32_e32 v169, 0x358637bd
	v_fmamk_f32 v168, v168, 0x3a000000, v169
	v_cmp_gt_f32_e32 vcc, 0xf800000, v168
	v_mul_f32_e32 v169, 0x4f800000, v168
	s_nop 0
	v_cndmask_b32_e32 v168, v168, v169, vcc
	v_sqrt_f32_e32 v169, v168
	s_nop 0
	v_add_u32_e32 v170, -1, v169
	v_fma_f32 v171, -v170, v169, v168
	v_cmp_ge_f32_e64 s[100:101], 0, v171
	v_add_u32_e32 v171, 1, v169
	s_nop 0
	v_cndmask_b32_e64 v170, v169, v170, s[100:101]
	v_fma_f32 v169, -v171, v169, v168
	v_cmp_lt_f32_e64 s[100:101], 0, v169
	s_nop 1
	v_cndmask_b32_e64 v169, v170, v171, s[100:101]
	v_mul_f32_e32 v170, 0x37800000, v169
	v_cndmask_b32_e32 v169, v169, v170, vcc
	v_mov_b32_e32 v170, 0x260
	v_cmp_class_f32_e32 vcc, v168, v170
	s_nop 1
	v_cndmask_b32_e32 v168, v169, v168, vcc
	v_div_scale_f32 v169, s[100:101], v168, v168, 1.0
	v_rcp_f32_e32 v170, v169
	s_nop 0
	v_fma_f32 v171, -v169, v170, 1.0
	v_fmac_f32_e32 v170, v171, v170
	v_div_scale_f32 v171, vcc, 1.0, v168, 1.0
	v_mul_f32_e32 v172, v171, v170
	v_fma_f32 v173, -v169, v172, v171
	v_fmac_f32_e32 v172, v173, v170
	v_fma_f32 v169, -v169, v172, v171
	s_nop 0
	v_div_fmas_f32 v169, v169, v170, v172
	v_div_fixup_f32 v172, v169, v168, 1.0
	s_lshl_b32 s101, s4, 13
	s_add_u32 s12, s2, s101
	s_addc_u32 s13, s3, 0
	v_pk_mul_f32 v[0:1], v[0:1], v[172:173] op_sel_hi:[1,0]
	v_pk_mul_f32 v[2:3], v[2:3], v[172:173] op_sel_hi:[1,0]
	v_pk_mul_f32 v[0:1], v[64:65], v[0:1]
	v_pk_mul_f32 v[2:3], v[66:67], v[2:3]
	global_store_dwordx4 v160, v[0:3], s[12:13] offset:-4096 nt
	v_pk_mul_f32 v[4:5], v[4:5], v[172:173] op_sel_hi:[1,0]
	v_pk_mul_f32 v[6:7], v[6:7], v[172:173] op_sel_hi:[1,0]
	v_pk_mul_f32 v[4:5], v[68:69], v[4:5]
	v_pk_mul_f32 v[6:7], v[70:71], v[6:7]
	global_store_dwordx4 v160, v[4:7], s[12:13] offset:-3072 nt
	v_pk_mul_f32 v[8:9], v[8:9], v[172:173] op_sel_hi:[1,0]
	v_pk_mul_f32 v[10:11], v[10:11], v[172:173] op_sel_hi:[1,0]
	v_pk_mul_f32 v[8:9], v[72:73], v[8:9]
	v_pk_mul_f32 v[10:11], v[74:75], v[10:11]
	global_store_dwordx4 v160, v[8:11], s[12:13] offset:-2048 nt
	v_pk_mul_f32 v[12:13], v[12:13], v[172:173] op_sel_hi:[1,0]
	v_pk_mul_f32 v[14:15], v[14:15], v[172:173] op_sel_hi:[1,0]
	v_pk_mul_f32 v[12:13], v[76:77], v[12:13]
	v_pk_mul_f32 v[14:15], v[78:79], v[14:15]
	global_store_dwordx4 v160, v[12:15], s[12:13] offset:-1024 nt
	v_pk_mul_f32 v[16:17], v[16:17], v[172:173] op_sel_hi:[1,0]
	v_pk_mul_f32 v[18:19], v[18:19], v[172:173] op_sel_hi:[1,0]
	v_pk_mul_f32 v[16:17], v[80:81], v[16:17]
	v_pk_mul_f32 v[18:19], v[82:83], v[18:19]
	global_store_dwordx4 v160, v[16:19], s[12:13] offset:0 nt
	v_pk_mul_f32 v[20:21], v[20:21], v[172:173] op_sel_hi:[1,0]
	v_pk_mul_f32 v[22:23], v[22:23], v[172:173] op_sel_hi:[1,0]
	v_pk_mul_f32 v[20:21], v[84:85], v[20:21]
	v_pk_mul_f32 v[22:23], v[86:87], v[22:23]
	global_store_dwordx4 v160, v[20:23], s[12:13] offset:1024 nt
	v_pk_mul_f32 v[24:25], v[24:25], v[172:173] op_sel_hi:[1,0]
	v_pk_mul_f32 v[26:27], v[26:27], v[172:173] op_sel_hi:[1,0]
	v_pk_mul_f32 v[24:25], v[88:89], v[24:25]
	v_pk_mul_f32 v[26:27], v[90:91], v[26:27]
	global_store_dwordx4 v160, v[24:27], s[12:13] offset:2048 nt
	v_pk_mul_f32 v[28:29], v[28:29], v[172:173] op_sel_hi:[1,0]
	v_pk_mul_f32 v[30:31], v[30:31], v[172:173] op_sel_hi:[1,0]
	v_pk_mul_f32 v[28:29], v[92:93], v[28:29]
	v_pk_mul_f32 v[30:31], v[94:95], v[30:31]
	global_store_dwordx4 v160, v[28:31], s[12:13] offset:3072 nt
	s_mov_b32 s4, s5
	s_cmp_lt_i32 s4, 0x4000
	s_cbranch_scc1 .Lhf_it_b
